# de-serialised global loads: s5 GLU weight loads kept 16 in flight; lru conv z-row loads issued together (on top of XCD-local barriers)
# speedup vs baseline: 1.0174x; 1.0174x over previous
; template <bool FULL> __device__ __forceinline__ void lru_tile(const Args& a, int l, int tile, LAS unsigned char* lds, int tid, int lane, int wave) {
;     ...
;     for (int it = 0; it < 4; ++it) {
;         const int ch = it * NTHR + tid, t = ch >> 5, c8 = ch & 31;
;         float xc[8];
;         { const f32x4 b0 = *(const f32x4*)(a.in[20] + (size_t)l * 256 + c8 * 8), b1 = *(const f32x4*)(a.in[20] + (size_t)l * 256 + c8 * 8 + 4);
;           xc[0] = b0.x; xc[1] = b0.y; xc[2] = b0.z; xc[3] = b0.w; xc[4] = b1.x; xc[5] = b1.y; xc[6] = b1.z; xc[7] = b1.w; }
; #pragma unroll
;         for (int j = 0; j < 4; ++j) {
;             if (tloc0 + t + j - 3 >= 0) {
;                 const u32x4 v = *(const u32x4*)(Z + (size_t)(t0 + t + j - 3) * IW + 2304 + c8 * 8); float f[8]; unpack8(v, f);
;                 const f32x4 w0 = *(const f32x4*)(a.in[19] + ((size_t)l * 4 + j) * 256 + c8 * 8), w1 = *(const f32x4*)(a.in[19] + ((size_t)l * 4 + j) * 256 + c8 * 8 + 4);
;                 xc[0] = fmaf(w0.x, f[0], xc[0]); xc[1] = fmaf(w0.y, f[1], xc[1]); xc[2] = fmaf(w0.z, f[2], xc[2]); xc[3] = fmaf(w0.w, f[3], xc[3]);
;                 xc[4] = fmaf(w1.x, f[4], xc[4]); xc[5] = fmaf(w1.y, f[5], xc[5]); xc[6] = fmaf(w1.z, f[6], xc[6]); xc[7] = fmaf(w1.w, f[7], xc[7]);
;             }
.LBB0_1291:
	v_ashrrev_i32_e32 v186, 5, v76
	s_add_i32 s26, s24, -3
	v_add_u32_e32 v186, s26, v186
	v_lshlrev_b32_e32 v188, 4, v76
	v_and_b32_e32 v188, 0x1f0, v188
	v_mov_b32_e32 v189, 0
	v_mov_b64_e32 v[190:191], s[20:21]
	s_nop 0
	v_mad_i64_i32 v[190:191], s[26:27], v186, s84, v[190:191]
	s_mov_b32 s26, 0xd601200
	s_mov_b32 s27, 0
	v_lshl_add_u64 v[190:191], v[190:191], 0, v[188:189]
	v_lshl_add_u64 v[190:191], v[190:191], 0, s[26:27]
	s_movk_i32 s26, 0x1600
	global_load_dwordx4 v[198:201], v[190:191], off
	v_lshl_add_u64 v[190:191], v[190:191], 0, s[26:27]
	global_load_dwordx4 v[202:205], v[190:191], off
	v_lshl_add_u64 v[190:191], v[190:191], 0, s[26:27]
	global_load_dwordx4 v[206:209], v[190:191], off
	v_lshl_add_u64 v[190:191], v[190:191], 0, s[26:27]
	global_load_dwordx4 v[210:213], v[190:191], off
	s_mov_b32 s26, 0x11e00
	v_lshl_add_u64 v[190:191], v[190:191], 0, s[26:27]
	s_movk_i32 s26, 0x1600
	global_load_dwordx4 v[214:217], v[190:191], off
	v_lshl_add_u64 v[190:191], v[190:191], 0, s[26:27]
	global_load_dwordx4 v[218:221], v[190:191], off
	v_lshl_add_u64 v[190:191], v[190:191], 0, s[26:27]
	global_load_dwordx4 v[222:225], v[190:191], off
	v_lshl_add_u64 v[190:191], v[190:191], 0, s[26:27]
	global_load_dwordx4 v[226:229], v[190:191], off
	s_mov_b32 s26, 0x11e00
	v_lshl_add_u64 v[190:191], v[190:191], 0, s[26:27]
	s_movk_i32 s26, 0x1600
	global_load_dwordx4 v[230:233], v[190:191], off
	v_lshl_add_u64 v[190:191], v[190:191], 0, s[26:27]
	global_load_dwordx4 v[234:237], v[190:191], off
	v_lshl_add_u64 v[190:191], v[190:191], 0, s[26:27]
	global_load_dwordx4 v[238:241], v[190:191], off
	v_lshl_add_u64 v[190:191], v[190:191], 0, s[26:27]
	global_load_dwordx4 v[242:245], v[190:191], off
	s_mov_b32 s26, 0x11e00
	v_lshl_add_u64 v[190:191], v[190:191], 0, s[26:27]
	s_movk_i32 s26, 0x1600
	global_load_dwordx4 v[246:249], v[190:191], off
	v_lshl_add_u64 v[190:191], v[190:191], 0, s[26:27]
	global_load_dwordx4 v[150:153], v[190:191], off
	v_lshl_add_u64 v[190:191], v[190:191], 0, s[26:27]
	global_load_dwordx4 v[154:157], v[190:191], off
	v_lshl_add_u64 v[190:191], v[190:191], 0, s[26:27]
	global_load_dwordx4 v[158:161], v[190:191], off
	v_lshlrev_b32_e32 v0, 3, v76
	v_and_b32_e32 v8, 0xf8, v0
	v_readlane_b32 s0, v254, 37
	v_lshlrev_b32_e32 v144, 2, v8
	v_readlane_b32 s1, v254, 38
	s_barrier
	s_nop 3
	global_load_dwordx4 v[0:3], v144, s[0:1] offset:16
	global_load_dwordx4 v[4:7], v144, s[0:1]
	s_and_b32 s4, s24, 0x1fc0
	v_ashrrev_i32_e32 v9, 5, v76
	v_readlane_b32 s0, v254, 39
	s_add_i32 s5, s24, -3
	v_add_u32_e32 v14, s4, v9
	v_readlane_b32 s1, v254, 40
	v_add_u32_e32 v15, s5, v9
	v_cmp_lt_i32_e32 vcc, 2, v14
	v_lshl_add_u64 v[10:11], s[0:1], 0, v[144:145]
	v_lshlrev_b32_e32 v12, 1, v8
	s_and_saveexec_b64 s[0:1], vcc
	s_cbranch_execz .LBB0_1295
	v_mov_b64_e32 v[16:17], s[20:21]
	v_mad_i64_i32 v[16:17], s[26:27], v15, s84, v[16:17]
	v_mov_b32_e32 v13, v145
	v_lshl_add_u64 v[16:17], v[16:17], 0, v[12:13]
	v_add_co_u32_e32 v16, vcc, 0xd601000, v16
	s_nop 1
	v_addc_co_u32_e32 v17, vcc, 0, v17, vcc
	s_waitcnt vmcnt(0)
	v_lshlrev_b32_e32 v24, 16, v198
	v_and_b32_e32 v25, 0xffff0000, v198
	v_lshlrev_b32_e32 v26, 16, v199
	v_and_b32_e32 v27, 0xffff0000, v199
	v_lshlrev_b32_e32 v28, 16, v200
	v_and_b32_e32 v29, 0xffff0000, v200
	v_lshlrev_b32_e32 v30, 16, v201
	v_and_b32_e32 v31, 0xffff0000, v201
	global_load_dwordx4 v[16:19], v[10:11], off offset:16
	global_load_dwordx4 v[20:23], v[10:11], off
	s_waitcnt vmcnt(1)
	v_pk_fma_f32 v[0:1], v[16:17], v[28:29], v[0:1]
	s_waitcnt vmcnt(0)
	v_pk_fma_f32 v[4:5], v[20:21], v[24:25], v[4:5]
	v_pk_fma_f32 v[6:7], v[22:23], v[26:27], v[6:7]
	v_pk_fma_f32 v[2:3], v[18:19], v[30:31], v[2:3]
	s_or_b64 exec, exec, s[0:1]
	v_cmp_lt_i32_e32 vcc, 1, v14
	s_and_saveexec_b64 s[0:1], vcc
	s_cbranch_execnz .LBB0_1296

; template <bool FULL> __device__ __forceinline__ void lru_tile(const Args& a, int l, int tile, LAS unsigned char* lds, int tid, int lane, int wave) {
;     ...
;         for (int j = 0; j < 4; ++j) {
;             if (tloc0 + t + j - 3 >= 0) {
;                 const u32x4 v = *(const u32x4*)(Z + (size_t)(t0 + t + j - 3) * IW + 2304 + c8 * 8); float f[8]; unpack8(v, f);
;                 const f32x4 w0 = *(const f32x4*)(a.in[19] + ((size_t)l * 4 + j) * 256 + c8 * 8), w1 = *(const f32x4*)(a.in[19] + ((size_t)l * 4 + j) * 256 + c8 * 8 + 4);
;                 xc[0] = fmaf(w0.x, f[0], xc[0]); xc[1] = fmaf(w0.y, f[1], xc[1]); xc[2] = fmaf(w0.z, f[2], xc[2]); xc[3] = fmaf(w0.w, f[3], xc[3]);
;                 xc[4] = fmaf(w1.x, f[4], xc[4]); xc[5] = fmaf(w1.y, f[5], xc[5]); xc[6] = fmaf(w1.z, f[6], xc[6]); xc[7] = fmaf(w1.w, f[7], xc[7]);
;             }
.LBB0_1294:
	v_add_u32_e32 v13, 2, v15
	v_mov_b64_e32 v[16:17], s[20:21]
	v_mad_i64_i32 v[16:17], s[26:27], v13, s84, v[16:17]
	v_mov_b32_e32 v13, v145
	v_lshl_add_u64 v[16:17], v[16:17], 0, v[12:13]
	v_add_co_u32_e32 v16, vcc, 0xd601000, v16
	s_nop 1
	v_addc_co_u32_e32 v17, vcc, 0, v17, vcc
	s_waitcnt vmcnt(0)
	v_lshlrev_b32_e32 v24, 16, v206
	v_and_b32_e32 v25, 0xffff0000, v206
	v_lshlrev_b32_e32 v26, 16, v207
	v_and_b32_e32 v27, 0xffff0000, v207
	v_lshlrev_b32_e32 v28, 16, v208
	v_and_b32_e32 v29, 0xffff0000, v208
	v_lshlrev_b32_e32 v30, 16, v209
	v_and_b32_e32 v31, 0xffff0000, v209
	global_load_dwordx4 v[16:19], v[10:11], off offset:2064
	global_load_dwordx4 v[20:23], v[10:11], off offset:2048
	s_waitcnt vmcnt(1)
	v_pk_fma_f32 v[0:1], v[16:17], v[28:29], v[0:1]
	s_waitcnt vmcnt(0)
	v_pk_fma_f32 v[4:5], v[20:21], v[24:25], v[4:5]
	v_pk_fma_f32 v[6:7], v[22:23], v[26:27], v[6:7]
	v_pk_fma_f32 v[2:3], v[18:19], v[30:31], v[2:3]
	s_or_b64 exec, exec, s[0:1]
	v_cmp_lt_i32_e32 vcc, -1, v14
	s_and_saveexec_b64 s[0:1], vcc
	s_cbranch_execnz .LBB0_1298
	s_branch .LBB0_1299

; template <bool FULL> __device__ __forceinline__ void lru_tile(const Args& a, int l, int tile, LAS unsigned char* lds, int tid, int lane, int wave) {
;     ...
;         for (int j = 0; j < 4; ++j) {
;             if (tloc0 + t + j - 3 >= 0) {
;                 const u32x4 v = *(const u32x4*)(Z + (size_t)(t0 + t + j - 3) * IW + 2304 + c8 * 8); float f[8]; unpack8(v, f);
;                 const f32x4 w0 = *(const f32x4*)(a.in[19] + ((size_t)l * 4 + j) * 256 + c8 * 8), w1 = *(const f32x4*)(a.in[19] + ((size_t)l * 4 + j) * 256 + c8 * 8 + 4);
;                 xc[0] = fmaf(w0.x, f[0], xc[0]); xc[1] = fmaf(w0.y, f[1], xc[1]); xc[2] = fmaf(w0.z, f[2], xc[2]); xc[3] = fmaf(w0.w, f[3], xc[3]);
;                 xc[4] = fmaf(w1.x, f[4], xc[4]); xc[5] = fmaf(w1.y, f[5], xc[5]); xc[6] = fmaf(w1.z, f[6], xc[6]); xc[7] = fmaf(w1.w, f[7], xc[7]);
;             }
.LBB0_1296:
	v_add_u32_e32 v13, 1, v15
	v_mov_b64_e32 v[16:17], s[20:21]
	v_mad_i64_i32 v[16:17], s[26:27], v13, s84, v[16:17]
	v_mov_b32_e32 v13, v145
	v_lshl_add_u64 v[16:17], v[16:17], 0, v[12:13]
	v_add_co_u32_e32 v16, vcc, 0xd601000, v16
	s_nop 1
	v_addc_co_u32_e32 v17, vcc, 0, v17, vcc
	s_waitcnt vmcnt(0)
	v_lshlrev_b32_e32 v24, 16, v202
	v_and_b32_e32 v25, 0xffff0000, v202
	v_lshlrev_b32_e32 v26, 16, v203
	v_and_b32_e32 v27, 0xffff0000, v203
	v_lshlrev_b32_e32 v28, 16, v204
	v_and_b32_e32 v29, 0xffff0000, v204
	v_lshlrev_b32_e32 v30, 16, v205
	v_and_b32_e32 v31, 0xffff0000, v205
	global_load_dwordx4 v[16:19], v[10:11], off offset:1040
	global_load_dwordx4 v[20:23], v[10:11], off offset:1024
	s_waitcnt vmcnt(1)
	v_pk_fma_f32 v[0:1], v[16:17], v[28:29], v[0:1]
	s_waitcnt vmcnt(0)
	v_pk_fma_f32 v[4:5], v[20:21], v[24:25], v[4:5]
	v_pk_fma_f32 v[6:7], v[22:23], v[26:27], v[6:7]
	v_pk_fma_f32 v[2:3], v[18:19], v[30:31], v[2:3]
	s_or_b64 exec, exec, s[0:1]
	v_cmp_lt_i32_e32 vcc, 0, v14
	s_and_saveexec_b64 s[0:1], vcc
	s_cbranch_execnz .LBB0_1294

; #define LAS __attribute__((address_space(3)))
; __device__ __forceinline__ unsigned pk2(float lo, float hi) { return pg8::cvt_pk_bf16(lo, hi); }
; template <bool FULL> __device__ __forceinline__ void lru_tile(const Args& a, int l, int tile, LAS unsigned char* lds, int tid, int lane, int wave) {
;     ...
;         for (int j = 0; j < 4; ++j) {
;             if (tloc0 + t + j - 3 >= 0) {
;                 const u32x4 v = *(const u32x4*)(Z + (size_t)(t0 + t + j - 3) * IW + 2304 + c8 * 8); float f[8]; unpack8(v, f);
;                 const f32x4 w0 = *(const f32x4*)(a.in[19] + ((size_t)l * 4 + j) * 256 + c8 * 8), w1 = *(const f32x4*)(a.in[19] + ((size_t)l * 4 + j) * 256 + c8 * 8 + 4);
;                 xc[0] = fmaf(w0.x, f[0], xc[0]); xc[1] = fmaf(w0.y, f[1], xc[1]); xc[2] = fmaf(w0.z, f[2], xc[2]); xc[3] = fmaf(w0.w, f[3], xc[3]);
;                 xc[4] = fmaf(w1.x, f[4], xc[4]); xc[5] = fmaf(w1.y, f[5], xc[5]); xc[6] = fmaf(w1.z, f[6], xc[6]); xc[7] = fmaf(w1.w, f[7], xc[7]);
;             }
;         }
;         u32x4 w; w.x = pk2(xc[0], xc[1]); w.y = pk2(xc[2], xc[3]); w.z = pk2(xc[4], xc[5]); w.w = pk2(xc[6], xc[7]);
;         *(LAS u32x4*)(lds + OFF_XC + (t * 264 + c8 * 8) * 2) = w;
.LBB0_1298:
	v_add_u32_e32 v13, s24, v9
	v_mov_b64_e32 v[14:15], s[20:21]
	v_mad_i64_i32 v[14:15], s[26:27], v13, s84, v[14:15]
	v_mov_b32_e32 v13, v145
	v_lshl_add_u64 v[14:15], v[14:15], 0, v[12:13]
	v_add_co_u32_e32 v14, vcc, 0xd601000, v14
	s_nop 1
	v_addc_co_u32_e32 v15, vcc, 0, v15, vcc
	s_waitcnt vmcnt(0)
	v_lshlrev_b32_e32 v22, 16, v210
	v_and_b32_e32 v23, 0xffff0000, v210
	v_lshlrev_b32_e32 v24, 16, v211
	v_and_b32_e32 v25, 0xffff0000, v211
	v_lshlrev_b32_e32 v26, 16, v212
	v_and_b32_e32 v27, 0xffff0000, v212
	v_lshlrev_b32_e32 v28, 16, v213
	v_and_b32_e32 v29, 0xffff0000, v213
	global_load_dwordx4 v[14:17], v[10:11], off offset:3088
	global_load_dwordx4 v[18:21], v[10:11], off offset:3072
	s_waitcnt vmcnt(1)
	v_pk_fma_f32 v[0:1], v[14:15], v[26:27], v[0:1]
	s_waitcnt vmcnt(0)
	v_pk_fma_f32 v[4:5], v[18:19], v[22:23], v[4:5]
	v_pk_fma_f32 v[6:7], v[20:21], v[24:25], v[6:7]
	v_pk_fma_f32 v[2:3], v[16:17], v[28:29], v[2:3]
.LBB0_1299:
	s_or_b64 exec, exec, s[0:1]
	v_readlane_b32 s0, v254, 37
	v_readlane_b32 s1, v254, 38
	s_waitcnt vmcnt(0)
	v_cvt_pk_bf16_f32 v4, v4, v5
	v_cvt_pk_bf16_f32 v5, v6, v7
	v_cvt_pk_bf16_f32 v6, v0, v1
	v_cvt_pk_bf16_f32 v7, v2, v3
	s_nop 0
	v_lshl_add_u64 v[14:15], s[0:1], 0, v[144:145]
	v_mad_u64_u32 v[0:1], s[0:1], v9, s12, v[8:9]
	v_lshl_add_u32 v0, v0, 1, 0
	v_add_u32_e32 v0, 0x10000, v0
	ds_write_b128 v0, v[4:7]
	v_add_u32_e32 v0, 0x200, v76
	v_ashrrev_i32_e32 v9, 5, v0
	global_load_dwordx4 v[0:3], v[14:15], off offset:16
	global_load_dwordx4 v[4:7], v[14:15], off
	v_add_u32_e32 v16, s4, v9
	v_add_u32_e32 v17, s5, v9
	v_cmp_lt_i32_e32 vcc, 2, v16
	s_and_saveexec_b64 s[0:1], vcc
	s_cbranch_execz .LBB0_1303
	v_mov_b64_e32 v[18:19], s[20:21]
	v_mad_i64_i32 v[18:19], s[26:27], v17, s84, v[18:19]
	v_mov_b32_e32 v13, v145
	v_lshl_add_u64 v[18:19], v[18:19], 0, v[12:13]
	v_add_co_u32_e32 v18, vcc, 0xd601000, v18
	s_nop 1
	v_addc_co_u32_e32 v19, vcc, 0, v19, vcc
	s_waitcnt vmcnt(0)
	v_lshlrev_b32_e32 v26, 16, v214
	v_and_b32_e32 v27, 0xffff0000, v214
	v_lshlrev_b32_e32 v28, 16, v215
	v_and_b32_e32 v29, 0xffff0000, v215
	v_lshlrev_b32_e32 v30, 16, v216
	v_and_b32_e32 v31, 0xffff0000, v216
	v_lshlrev_b32_e32 v32, 16, v217
	v_and_b32_e32 v33, 0xffff0000, v217
	global_load_dwordx4 v[18:21], v[10:11], off offset:16
	global_load_dwordx4 v[22:25], v[10:11], off
	s_waitcnt vmcnt(1)
	v_pk_fma_f32 v[0:1], v[18:19], v[30:31], v[0:1]
	s_waitcnt vmcnt(0)
	v_pk_fma_f32 v[4:5], v[22:23], v[26:27], v[4:5]
	v_pk_fma_f32 v[6:7], v[24:25], v[28:29], v[6:7]
	v_pk_fma_f32 v[2:3], v[20:21], v[32:33], v[2:3]
	s_or_b64 exec, exec, s[0:1]
	v_cmp_lt_i32_e32 vcc, 1, v16
	s_and_saveexec_b64 s[0:1], vcc
	s_cbranch_execnz .LBB0_1304

; template <bool FULL> __device__ __forceinline__ void lru_tile(const Args& a, int l, int tile, LAS unsigned char* lds, int tid, int lane, int wave) {
;     ...
;         for (int j = 0; j < 4; ++j) {
;             if (tloc0 + t + j - 3 >= 0) {
;                 const u32x4 v = *(const u32x4*)(Z + (size_t)(t0 + t + j - 3) * IW + 2304 + c8 * 8); float f[8]; unpack8(v, f);
;                 const f32x4 w0 = *(const f32x4*)(a.in[19] + ((size_t)l * 4 + j) * 256 + c8 * 8), w1 = *(const f32x4*)(a.in[19] + ((size_t)l * 4 + j) * 256 + c8 * 8 + 4);
;                 xc[0] = fmaf(w0.x, f[0], xc[0]); xc[1] = fmaf(w0.y, f[1], xc[1]); xc[2] = fmaf(w0.z, f[2], xc[2]); xc[3] = fmaf(w0.w, f[3], xc[3]);
;                 xc[4] = fmaf(w1.x, f[4], xc[4]); xc[5] = fmaf(w1.y, f[5], xc[5]); xc[6] = fmaf(w1.z, f[6], xc[6]); xc[7] = fmaf(w1.w, f[7], xc[7]);
;             }
.LBB0_1302:
	v_add_u32_e32 v13, 2, v17
	v_mov_b64_e32 v[18:19], s[20:21]
	v_mad_i64_i32 v[18:19], s[26:27], v13, s84, v[18:19]
	v_mov_b32_e32 v13, v145
	v_lshl_add_u64 v[18:19], v[18:19], 0, v[12:13]
	v_add_co_u32_e32 v18, vcc, 0xd601000, v18
	s_nop 1
	v_addc_co_u32_e32 v19, vcc, 0, v19, vcc
	s_waitcnt vmcnt(0)
	v_lshlrev_b32_e32 v26, 16, v222
	v_and_b32_e32 v27, 0xffff0000, v222
	v_lshlrev_b32_e32 v28, 16, v223
	v_and_b32_e32 v29, 0xffff0000, v223
	v_lshlrev_b32_e32 v30, 16, v224
	v_and_b32_e32 v31, 0xffff0000, v224
	v_lshlrev_b32_e32 v32, 16, v225
	v_and_b32_e32 v33, 0xffff0000, v225
	global_load_dwordx4 v[18:21], v[10:11], off offset:2064
	global_load_dwordx4 v[22:25], v[10:11], off offset:2048
	s_waitcnt vmcnt(1)
	v_pk_fma_f32 v[0:1], v[18:19], v[30:31], v[0:1]
	s_waitcnt vmcnt(0)
	v_pk_fma_f32 v[4:5], v[22:23], v[26:27], v[4:5]
	v_pk_fma_f32 v[6:7], v[24:25], v[28:29], v[6:7]
	v_pk_fma_f32 v[2:3], v[20:21], v[32:33], v[2:3]
	s_or_b64 exec, exec, s[0:1]
	v_cmp_lt_i32_e32 vcc, -1, v16
	s_and_saveexec_b64 s[0:1], vcc
	s_cbranch_execnz .LBB0_1306
	s_branch .LBB0_1307

; template <bool FULL> __device__ __forceinline__ void lru_tile(const Args& a, int l, int tile, LAS unsigned char* lds, int tid, int lane, int wave) {
;     ...
;         for (int j = 0; j < 4; ++j) {
;             if (tloc0 + t + j - 3 >= 0) {
;                 const u32x4 v = *(const u32x4*)(Z + (size_t)(t0 + t + j - 3) * IW + 2304 + c8 * 8); float f[8]; unpack8(v, f);
;                 const f32x4 w0 = *(const f32x4*)(a.in[19] + ((size_t)l * 4 + j) * 256 + c8 * 8), w1 = *(const f32x4*)(a.in[19] + ((size_t)l * 4 + j) * 256 + c8 * 8 + 4);
;                 xc[0] = fmaf(w0.x, f[0], xc[0]); xc[1] = fmaf(w0.y, f[1], xc[1]); xc[2] = fmaf(w0.z, f[2], xc[2]); xc[3] = fmaf(w0.w, f[3], xc[3]);
;                 xc[4] = fmaf(w1.x, f[4], xc[4]); xc[5] = fmaf(w1.y, f[5], xc[5]); xc[6] = fmaf(w1.z, f[6], xc[6]); xc[7] = fmaf(w1.w, f[7], xc[7]);
;             }
.LBB0_1304:
	v_add_u32_e32 v13, 1, v17
	v_mov_b64_e32 v[18:19], s[20:21]
	v_mad_i64_i32 v[18:19], s[26:27], v13, s84, v[18:19]
	v_mov_b32_e32 v13, v145
	v_lshl_add_u64 v[18:19], v[18:19], 0, v[12:13]
	v_add_co_u32_e32 v18, vcc, 0xd601000, v18
	s_nop 1
	v_addc_co_u32_e32 v19, vcc, 0, v19, vcc
	s_waitcnt vmcnt(0)
	v_lshlrev_b32_e32 v26, 16, v218
	v_and_b32_e32 v27, 0xffff0000, v218
	v_lshlrev_b32_e32 v28, 16, v219
	v_and_b32_e32 v29, 0xffff0000, v219
	v_lshlrev_b32_e32 v30, 16, v220
	v_and_b32_e32 v31, 0xffff0000, v220
	v_lshlrev_b32_e32 v32, 16, v221
	v_and_b32_e32 v33, 0xffff0000, v221
	global_load_dwordx4 v[18:21], v[10:11], off offset:1040
	global_load_dwordx4 v[22:25], v[10:11], off offset:1024
	s_waitcnt vmcnt(1)
	v_pk_fma_f32 v[0:1], v[18:19], v[30:31], v[0:1]
	s_waitcnt vmcnt(0)
	v_pk_fma_f32 v[4:5], v[22:23], v[26:27], v[4:5]
	v_pk_fma_f32 v[6:7], v[24:25], v[28:29], v[6:7]
	v_pk_fma_f32 v[2:3], v[20:21], v[32:33], v[2:3]
	s_or_b64 exec, exec, s[0:1]
	v_cmp_lt_i32_e32 vcc, 0, v16
	s_and_saveexec_b64 s[0:1], vcc
	s_cbranch_execnz .LBB0_1302

; #define LAS __attribute__((address_space(3)))
; __device__ __forceinline__ unsigned pk2(float lo, float hi) { return pg8::cvt_pk_bf16(lo, hi); }
; template <bool FULL> __device__ __forceinline__ void lru_tile(const Args& a, int l, int tile, LAS unsigned char* lds, int tid, int lane, int wave) {
;     ...
;         for (int j = 0; j < 4; ++j) {
;             if (tloc0 + t + j - 3 >= 0) {
;                 const u32x4 v = *(const u32x4*)(Z + (size_t)(t0 + t + j - 3) * IW + 2304 + c8 * 8); float f[8]; unpack8(v, f);
;                 const f32x4 w0 = *(const f32x4*)(a.in[19] + ((size_t)l * 4 + j) * 256 + c8 * 8), w1 = *(const f32x4*)(a.in[19] + ((size_t)l * 4 + j) * 256 + c8 * 8 + 4);
;                 xc[0] = fmaf(w0.x, f[0], xc[0]); xc[1] = fmaf(w0.y, f[1], xc[1]); xc[2] = fmaf(w0.z, f[2], xc[2]); xc[3] = fmaf(w0.w, f[3], xc[3]);
;                 xc[4] = fmaf(w1.x, f[4], xc[4]); xc[5] = fmaf(w1.y, f[5], xc[5]); xc[6] = fmaf(w1.z, f[6], xc[6]); xc[7] = fmaf(w1.w, f[7], xc[7]);
;             }
;         }
;         u32x4 w; w.x = pk2(xc[0], xc[1]); w.y = pk2(xc[2], xc[3]); w.z = pk2(xc[4], xc[5]); w.w = pk2(xc[6], xc[7]);
;         *(LAS u32x4*)(lds + OFF_XC + (t * 264 + c8 * 8) * 2) = w;
.LBB0_1306:
	v_add_u32_e32 v13, s24, v9
	v_mov_b64_e32 v[16:17], s[20:21]
	v_mad_i64_i32 v[16:17], s[26:27], v13, s84, v[16:17]
	v_mov_b32_e32 v13, v145
	v_lshl_add_u64 v[16:17], v[16:17], 0, v[12:13]
	v_add_co_u32_e32 v16, vcc, 0xd601000, v16
	s_nop 1
	v_addc_co_u32_e32 v17, vcc, 0, v17, vcc
	s_waitcnt vmcnt(0)
	v_lshlrev_b32_e32 v24, 16, v226
	v_and_b32_e32 v25, 0xffff0000, v226
	v_lshlrev_b32_e32 v26, 16, v227
	v_and_b32_e32 v27, 0xffff0000, v227
	v_lshlrev_b32_e32 v28, 16, v228
	v_and_b32_e32 v29, 0xffff0000, v228
	v_lshlrev_b32_e32 v30, 16, v229
	v_and_b32_e32 v31, 0xffff0000, v229
	global_load_dwordx4 v[16:19], v[10:11], off offset:3088
	global_load_dwordx4 v[20:23], v[10:11], off offset:3072
	s_waitcnt vmcnt(1)
	v_pk_fma_f32 v[0:1], v[16:17], v[28:29], v[0:1]
	s_waitcnt vmcnt(0)
	v_pk_fma_f32 v[4:5], v[20:21], v[24:25], v[4:5]
	v_pk_fma_f32 v[6:7], v[22:23], v[26:27], v[6:7]
	v_pk_fma_f32 v[2:3], v[18:19], v[30:31], v[2:3]
.LBB0_1307:
	s_or_b64 exec, exec, s[0:1]
	s_waitcnt vmcnt(0)
	v_cvt_pk_bf16_f32 v4, v4, v5
	v_cvt_pk_bf16_f32 v5, v6, v7
	v_cvt_pk_bf16_f32 v6, v0, v1
	v_mad_u64_u32 v[0:1], s[0:1], v9, s12, v[8:9]
	v_lshl_add_u32 v0, v0, 1, 0
	v_add_u32_e32 v0, 0x10000, v0
	v_cvt_pk_bf16_f32 v7, v2, v3
	ds_write_b128 v0, v[4:7]
	v_add_u32_e32 v0, 0x400, v76
	v_ashrrev_i32_e32 v9, 5, v0
	global_load_dwordx4 v[0:3], v[14:15], off offset:16
	global_load_dwordx4 v[4:7], v[14:15], off
	v_add_u32_e32 v16, s4, v9
	v_add_u32_e32 v17, s5, v9
	v_cmp_lt_i32_e32 vcc, 2, v16
	s_and_saveexec_b64 s[0:1], vcc
	s_cbranch_execz .LBB0_1311
	v_mov_b64_e32 v[18:19], s[20:21]
	v_mad_i64_i32 v[18:19], s[26:27], v17, s84, v[18:19]
	v_mov_b32_e32 v13, v145
	v_lshl_add_u64 v[18:19], v[18:19], 0, v[12:13]
	v_add_co_u32_e32 v18, vcc, 0xd601000, v18
	s_nop 1
	v_addc_co_u32_e32 v19, vcc, 0, v19, vcc
	s_waitcnt vmcnt(0)
	v_lshlrev_b32_e32 v26, 16, v230
	v_and_b32_e32 v27, 0xffff0000, v230
	v_lshlrev_b32_e32 v28, 16, v231
	v_and_b32_e32 v29, 0xffff0000, v231
	v_lshlrev_b32_e32 v30, 16, v232
	v_and_b32_e32 v31, 0xffff0000, v232
	v_lshlrev_b32_e32 v32, 16, v233
	v_and_b32_e32 v33, 0xffff0000, v233
	global_load_dwordx4 v[18:21], v[10:11], off offset:16
	global_load_dwordx4 v[22:25], v[10:11], off
	s_waitcnt vmcnt(1)
	v_pk_fma_f32 v[0:1], v[18:19], v[30:31], v[0:1]
	s_waitcnt vmcnt(0)
	v_pk_fma_f32 v[4:5], v[22:23], v[26:27], v[4:5]
	v_pk_fma_f32 v[6:7], v[24:25], v[28:29], v[6:7]
	v_pk_fma_f32 v[2:3], v[20:21], v[32:33], v[2:3]
	s_or_b64 exec, exec, s[0:1]
	v_cmp_lt_i32_e32 vcc, 1, v16
	s_and_saveexec_b64 s[0:1], vcc
	s_cbranch_execnz .LBB0_1312

; template <bool FULL> __device__ __forceinline__ void lru_tile(const Args& a, int l, int tile, LAS unsigned char* lds, int tid, int lane, int wave) {
;     ...
;         for (int j = 0; j < 4; ++j) {
;             if (tloc0 + t + j - 3 >= 0) {
;                 const u32x4 v = *(const u32x4*)(Z + (size_t)(t0 + t + j - 3) * IW + 2304 + c8 * 8); float f[8]; unpack8(v, f);
;                 const f32x4 w0 = *(const f32x4*)(a.in[19] + ((size_t)l * 4 + j) * 256 + c8 * 8), w1 = *(const f32x4*)(a.in[19] + ((size_t)l * 4 + j) * 256 + c8 * 8 + 4);
;                 xc[0] = fmaf(w0.x, f[0], xc[0]); xc[1] = fmaf(w0.y, f[1], xc[1]); xc[2] = fmaf(w0.z, f[2], xc[2]); xc[3] = fmaf(w0.w, f[3], xc[3]);
;                 xc[4] = fmaf(w1.x, f[4], xc[4]); xc[5] = fmaf(w1.y, f[5], xc[5]); xc[6] = fmaf(w1.z, f[6], xc[6]); xc[7] = fmaf(w1.w, f[7], xc[7]);
;             }
.LBB0_1310:
	v_add_u32_e32 v13, 2, v17
	v_mov_b64_e32 v[18:19], s[20:21]
	v_mad_i64_i32 v[18:19], s[26:27], v13, s84, v[18:19]
	v_mov_b32_e32 v13, v145
	v_lshl_add_u64 v[18:19], v[18:19], 0, v[12:13]
	v_add_co_u32_e32 v18, vcc, 0xd601000, v18
	s_nop 1
	v_addc_co_u32_e32 v19, vcc, 0, v19, vcc
	s_waitcnt vmcnt(0)
	v_lshlrev_b32_e32 v26, 16, v238
	v_and_b32_e32 v27, 0xffff0000, v238
	v_lshlrev_b32_e32 v28, 16, v239
	v_and_b32_e32 v29, 0xffff0000, v239
	v_lshlrev_b32_e32 v30, 16, v240
	v_and_b32_e32 v31, 0xffff0000, v240
	v_lshlrev_b32_e32 v32, 16, v241
	v_and_b32_e32 v33, 0xffff0000, v241
	global_load_dwordx4 v[18:21], v[10:11], off offset:2064
	global_load_dwordx4 v[22:25], v[10:11], off offset:2048
	s_waitcnt vmcnt(1)
	v_pk_fma_f32 v[0:1], v[18:19], v[30:31], v[0:1]
	s_waitcnt vmcnt(0)
	v_pk_fma_f32 v[4:5], v[22:23], v[26:27], v[4:5]
	v_pk_fma_f32 v[6:7], v[24:25], v[28:29], v[6:7]
	v_pk_fma_f32 v[2:3], v[20:21], v[32:33], v[2:3]
	s_or_b64 exec, exec, s[0:1]
	v_cmp_lt_i32_e32 vcc, -1, v16
	s_and_saveexec_b64 s[0:1], vcc
	s_cbranch_execnz .LBB0_1314
	s_branch .LBB0_1315

; template <bool FULL> __device__ __forceinline__ void lru_tile(const Args& a, int l, int tile, LAS unsigned char* lds, int tid, int lane, int wave) {
;     ...
;         for (int j = 0; j < 4; ++j) {
;             if (tloc0 + t + j - 3 >= 0) {
;                 const u32x4 v = *(const u32x4*)(Z + (size_t)(t0 + t + j - 3) * IW + 2304 + c8 * 8); float f[8]; unpack8(v, f);
;                 const f32x4 w0 = *(const f32x4*)(a.in[19] + ((size_t)l * 4 + j) * 256 + c8 * 8), w1 = *(const f32x4*)(a.in[19] + ((size_t)l * 4 + j) * 256 + c8 * 8 + 4);
;                 xc[0] = fmaf(w0.x, f[0], xc[0]); xc[1] = fmaf(w0.y, f[1], xc[1]); xc[2] = fmaf(w0.z, f[2], xc[2]); xc[3] = fmaf(w0.w, f[3], xc[3]);
;                 xc[4] = fmaf(w1.x, f[4], xc[4]); xc[5] = fmaf(w1.y, f[5], xc[5]); xc[6] = fmaf(w1.z, f[6], xc[6]); xc[7] = fmaf(w1.w, f[7], xc[7]);
;             }
.LBB0_1312:
	v_add_u32_e32 v13, 1, v17
	v_mov_b64_e32 v[18:19], s[20:21]
	v_mad_i64_i32 v[18:19], s[26:27], v13, s84, v[18:19]
	v_mov_b32_e32 v13, v145
	v_lshl_add_u64 v[18:19], v[18:19], 0, v[12:13]
	v_add_co_u32_e32 v18, vcc, 0xd601000, v18
	s_nop 1
	v_addc_co_u32_e32 v19, vcc, 0, v19, vcc
	s_waitcnt vmcnt(0)
	v_lshlrev_b32_e32 v26, 16, v234
	v_and_b32_e32 v27, 0xffff0000, v234
	v_lshlrev_b32_e32 v28, 16, v235
	v_and_b32_e32 v29, 0xffff0000, v235
	v_lshlrev_b32_e32 v30, 16, v236
	v_and_b32_e32 v31, 0xffff0000, v236
	v_lshlrev_b32_e32 v32, 16, v237
	v_and_b32_e32 v33, 0xffff0000, v237
	global_load_dwordx4 v[18:21], v[10:11], off offset:1040
	global_load_dwordx4 v[22:25], v[10:11], off offset:1024
	s_waitcnt vmcnt(1)
	v_pk_fma_f32 v[0:1], v[18:19], v[30:31], v[0:1]
	s_waitcnt vmcnt(0)
	v_pk_fma_f32 v[4:5], v[22:23], v[26:27], v[4:5]
	v_pk_fma_f32 v[6:7], v[24:25], v[28:29], v[6:7]
	v_pk_fma_f32 v[2:3], v[20:21], v[32:33], v[2:3]
	s_or_b64 exec, exec, s[0:1]
	v_cmp_lt_i32_e32 vcc, 0, v16
	s_and_saveexec_b64 s[0:1], vcc
	s_cbranch_execnz .LBB0_1310

; #define LAS __attribute__((address_space(3)))
; __device__ __forceinline__ unsigned pk2(float lo, float hi) { return pg8::cvt_pk_bf16(lo, hi); }
; template <bool FULL> __device__ __forceinline__ void lru_tile(const Args& a, int l, int tile, LAS unsigned char* lds, int tid, int lane, int wave) {
;     ...
;         for (int j = 0; j < 4; ++j) {
;             if (tloc0 + t + j - 3 >= 0) {
;                 const u32x4 v = *(const u32x4*)(Z + (size_t)(t0 + t + j - 3) * IW + 2304 + c8 * 8); float f[8]; unpack8(v, f);
;                 const f32x4 w0 = *(const f32x4*)(a.in[19] + ((size_t)l * 4 + j) * 256 + c8 * 8), w1 = *(const f32x4*)(a.in[19] + ((size_t)l * 4 + j) * 256 + c8 * 8 + 4);
;                 xc[0] = fmaf(w0.x, f[0], xc[0]); xc[1] = fmaf(w0.y, f[1], xc[1]); xc[2] = fmaf(w0.z, f[2], xc[2]); xc[3] = fmaf(w0.w, f[3], xc[3]);
;                 xc[4] = fmaf(w1.x, f[4], xc[4]); xc[5] = fmaf(w1.y, f[5], xc[5]); xc[6] = fmaf(w1.z, f[6], xc[6]); xc[7] = fmaf(w1.w, f[7], xc[7]);
;             }
;         }
;         u32x4 w; w.x = pk2(xc[0], xc[1]); w.y = pk2(xc[2], xc[3]); w.z = pk2(xc[4], xc[5]); w.w = pk2(xc[6], xc[7]);
;         *(LAS u32x4*)(lds + OFF_XC + (t * 264 + c8 * 8) * 2) = w;
.LBB0_1314:
	v_add_u32_e32 v13, s24, v9
	v_mov_b64_e32 v[16:17], s[20:21]
	v_mad_i64_i32 v[16:17], s[26:27], v13, s84, v[16:17]
	v_mov_b32_e32 v13, v145
	v_lshl_add_u64 v[16:17], v[16:17], 0, v[12:13]
	v_add_co_u32_e32 v16, vcc, 0xd601000, v16
	s_nop 1
	v_addc_co_u32_e32 v17, vcc, 0, v17, vcc
	s_waitcnt vmcnt(0)
	v_lshlrev_b32_e32 v24, 16, v242
	v_and_b32_e32 v25, 0xffff0000, v242
	v_lshlrev_b32_e32 v26, 16, v243
	v_and_b32_e32 v27, 0xffff0000, v243
	v_lshlrev_b32_e32 v28, 16, v244
	v_and_b32_e32 v29, 0xffff0000, v244
	v_lshlrev_b32_e32 v30, 16, v245
	v_and_b32_e32 v31, 0xffff0000, v245
	global_load_dwordx4 v[16:19], v[10:11], off offset:3088
	global_load_dwordx4 v[20:23], v[10:11], off offset:3072
	s_waitcnt vmcnt(1)
	v_pk_fma_f32 v[0:1], v[16:17], v[28:29], v[0:1]
	s_waitcnt vmcnt(0)
	v_pk_fma_f32 v[4:5], v[20:21], v[24:25], v[4:5]
	v_pk_fma_f32 v[6:7], v[22:23], v[26:27], v[6:7]
	v_pk_fma_f32 v[2:3], v[18:19], v[30:31], v[2:3]
.LBB0_1315:
	s_or_b64 exec, exec, s[0:1]
	s_waitcnt vmcnt(0)
	v_cvt_pk_bf16_f32 v4, v4, v5
	v_cvt_pk_bf16_f32 v5, v6, v7
	v_cvt_pk_bf16_f32 v6, v0, v1
	v_mad_u64_u32 v[0:1], s[0:1], v9, s12, v[8:9]
	v_lshl_add_u32 v0, v0, 1, 0
	v_add_u32_e32 v0, 0x10000, v0
	v_cvt_pk_bf16_f32 v7, v2, v3
	ds_write_b128 v0, v[4:7]
	v_add_u32_e32 v0, 0x600, v76
	v_ashrrev_i32_e32 v9, 5, v0
	global_load_dwordx4 v[0:3], v[14:15], off offset:16
	global_load_dwordx4 v[4:7], v[14:15], off
	v_add_u32_e32 v14, s4, v9
	v_add_u32_e32 v15, s5, v9
	v_cmp_lt_i32_e32 vcc, 2, v14
	s_and_saveexec_b64 s[0:1], vcc
	s_cbranch_execz .LBB0_1319
	v_mov_b64_e32 v[16:17], s[20:21]
	v_mad_i64_i32 v[16:17], s[4:5], v15, s84, v[16:17]
	v_mov_b32_e32 v13, v145
	v_lshl_add_u64 v[16:17], v[16:17], 0, v[12:13]
	v_add_co_u32_e32 v16, vcc, 0xd601000, v16
	s_nop 1
	v_addc_co_u32_e32 v17, vcc, 0, v17, vcc
	s_waitcnt vmcnt(0)
	v_lshlrev_b32_e32 v24, 16, v246
	v_and_b32_e32 v25, 0xffff0000, v246
	v_lshlrev_b32_e32 v26, 16, v247
	v_and_b32_e32 v27, 0xffff0000, v247
	v_lshlrev_b32_e32 v28, 16, v248
	v_and_b32_e32 v29, 0xffff0000, v248
	v_lshlrev_b32_e32 v30, 16, v249
	v_and_b32_e32 v31, 0xffff0000, v249
	global_load_dwordx4 v[16:19], v[10:11], off offset:16
	global_load_dwordx4 v[20:23], v[10:11], off
	s_waitcnt vmcnt(1)
	v_pk_fma_f32 v[0:1], v[16:17], v[28:29], v[0:1]
	s_waitcnt vmcnt(0)
	v_pk_fma_f32 v[4:5], v[20:21], v[24:25], v[4:5]
	v_pk_fma_f32 v[6:7], v[22:23], v[26:27], v[6:7]
	v_pk_fma_f32 v[2:3], v[18:19], v[30:31], v[2:3]
	s_or_b64 exec, exec, s[0:1]
	v_cmp_lt_i32_e32 vcc, 1, v14
	s_and_saveexec_b64 s[0:1], vcc
	s_cbranch_execnz .LBB0_1320

; template <bool FULL> __device__ __forceinline__ void lru_tile(const Args& a, int l, int tile, LAS unsigned char* lds, int tid, int lane, int wave) {
;     ...
;         for (int j = 0; j < 4; ++j) {
;             if (tloc0 + t + j - 3 >= 0) {
;                 const u32x4 v = *(const u32x4*)(Z + (size_t)(t0 + t + j - 3) * IW + 2304 + c8 * 8); float f[8]; unpack8(v, f);
;                 const f32x4 w0 = *(const f32x4*)(a.in[19] + ((size_t)l * 4 + j) * 256 + c8 * 8), w1 = *(const f32x4*)(a.in[19] + ((size_t)l * 4 + j) * 256 + c8 * 8 + 4);
;                 xc[0] = fmaf(w0.x, f[0], xc[0]); xc[1] = fmaf(w0.y, f[1], xc[1]); xc[2] = fmaf(w0.z, f[2], xc[2]); xc[3] = fmaf(w0.w, f[3], xc[3]);
;                 xc[4] = fmaf(w1.x, f[4], xc[4]); xc[5] = fmaf(w1.y, f[5], xc[5]); xc[6] = fmaf(w1.z, f[6], xc[6]); xc[7] = fmaf(w1.w, f[7], xc[7]);
;             }
.LBB0_1318:
	v_add_u32_e32 v13, 2, v15
	v_mov_b64_e32 v[16:17], s[20:21]
	v_mad_i64_i32 v[16:17], s[4:5], v13, s84, v[16:17]
	v_mov_b32_e32 v13, v145
	v_lshl_add_u64 v[16:17], v[16:17], 0, v[12:13]
	v_add_co_u32_e32 v16, vcc, 0xd601000, v16
	s_nop 1
	v_addc_co_u32_e32 v17, vcc, 0, v17, vcc
	s_waitcnt vmcnt(0)
	v_lshlrev_b32_e32 v24, 16, v154
	v_and_b32_e32 v25, 0xffff0000, v154
	v_lshlrev_b32_e32 v26, 16, v155
	v_and_b32_e32 v27, 0xffff0000, v155
	v_lshlrev_b32_e32 v28, 16, v156
	v_and_b32_e32 v29, 0xffff0000, v156
	v_lshlrev_b32_e32 v30, 16, v157
	v_and_b32_e32 v31, 0xffff0000, v157
	global_load_dwordx4 v[16:19], v[10:11], off offset:2064
	global_load_dwordx4 v[20:23], v[10:11], off offset:2048
	s_waitcnt vmcnt(1)
	v_pk_fma_f32 v[0:1], v[16:17], v[28:29], v[0:1]
	s_waitcnt vmcnt(0)
	v_pk_fma_f32 v[4:5], v[20:21], v[24:25], v[4:5]
	v_pk_fma_f32 v[6:7], v[22:23], v[26:27], v[6:7]
	v_pk_fma_f32 v[2:3], v[18:19], v[30:31], v[2:3]
	s_or_b64 exec, exec, s[0:1]
	v_cmp_lt_i32_e32 vcc, -1, v14
	s_and_saveexec_b64 s[0:1], vcc
	s_cbranch_execnz .LBB0_1322
	s_branch .LBB0_1323

; template <bool FULL> __device__ __forceinline__ void lru_tile(const Args& a, int l, int tile, LAS unsigned char* lds, int tid, int lane, int wave) {
;     ...
;         for (int j = 0; j < 4; ++j) {
;             if (tloc0 + t + j - 3 >= 0) {
;                 const u32x4 v = *(const u32x4*)(Z + (size_t)(t0 + t + j - 3) * IW + 2304 + c8 * 8); float f[8]; unpack8(v, f);
;                 const f32x4 w0 = *(const f32x4*)(a.in[19] + ((size_t)l * 4 + j) * 256 + c8 * 8), w1 = *(const f32x4*)(a.in[19] + ((size_t)l * 4 + j) * 256 + c8 * 8 + 4);
;                 xc[0] = fmaf(w0.x, f[0], xc[0]); xc[1] = fmaf(w0.y, f[1], xc[1]); xc[2] = fmaf(w0.z, f[2], xc[2]); xc[3] = fmaf(w0.w, f[3], xc[3]);
;                 xc[4] = fmaf(w1.x, f[4], xc[4]); xc[5] = fmaf(w1.y, f[5], xc[5]); xc[6] = fmaf(w1.z, f[6], xc[6]); xc[7] = fmaf(w1.w, f[7], xc[7]);
;             }
.LBB0_1320:
	v_add_u32_e32 v13, 1, v15
	v_mov_b64_e32 v[16:17], s[20:21]
	v_mad_i64_i32 v[16:17], s[4:5], v13, s84, v[16:17]
	v_mov_b32_e32 v13, v145
	v_lshl_add_u64 v[16:17], v[16:17], 0, v[12:13]
	v_add_co_u32_e32 v16, vcc, 0xd601000, v16
	s_nop 1
	v_addc_co_u32_e32 v17, vcc, 0, v17, vcc
	s_waitcnt vmcnt(0)
	v_lshlrev_b32_e32 v24, 16, v150
	v_and_b32_e32 v25, 0xffff0000, v150
	v_lshlrev_b32_e32 v26, 16, v151
	v_and_b32_e32 v27, 0xffff0000, v151
	v_lshlrev_b32_e32 v28, 16, v152
	v_and_b32_e32 v29, 0xffff0000, v152
	v_lshlrev_b32_e32 v30, 16, v153
	v_and_b32_e32 v31, 0xffff0000, v153
	global_load_dwordx4 v[16:19], v[10:11], off offset:1040
	global_load_dwordx4 v[20:23], v[10:11], off offset:1024
	s_waitcnt vmcnt(1)
	v_pk_fma_f32 v[0:1], v[16:17], v[28:29], v[0:1]
	s_waitcnt vmcnt(0)
	v_pk_fma_f32 v[4:5], v[20:21], v[24:25], v[4:5]
	v_pk_fma_f32 v[6:7], v[22:23], v[26:27], v[6:7]
	v_pk_fma_f32 v[2:3], v[18:19], v[30:31], v[2:3]
	s_or_b64 exec, exec, s[0:1]
	v_cmp_lt_i32_e32 vcc, 0, v14
	s_and_saveexec_b64 s[0:1], vcc
	s_cbranch_execnz .LBB0_1318

; template <bool FULL> __device__ __forceinline__ void lru_tile(const Args& a, int l, int tile, LAS unsigned char* lds, int tid, int lane, int wave) {
;     ...
;         for (int j = 0; j < 4; ++j) {
;             if (tloc0 + t + j - 3 >= 0) {
;                 const u32x4 v = *(const u32x4*)(Z + (size_t)(t0 + t + j - 3) * IW + 2304 + c8 * 8); float f[8]; unpack8(v, f);
;                 const f32x4 w0 = *(const f32x4*)(a.in[19] + ((size_t)l * 4 + j) * 256 + c8 * 8), w1 = *(const f32x4*)(a.in[19] + ((size_t)l * 4 + j) * 256 + c8 * 8 + 4);
;                 xc[0] = fmaf(w0.x, f[0], xc[0]); xc[1] = fmaf(w0.y, f[1], xc[1]); xc[2] = fmaf(w0.z, f[2], xc[2]); xc[3] = fmaf(w0.w, f[3], xc[3]);
;                 xc[4] = fmaf(w1.x, f[4], xc[4]); xc[5] = fmaf(w1.y, f[5], xc[5]); xc[6] = fmaf(w1.z, f[6], xc[6]); xc[7] = fmaf(w1.w, f[7], xc[7]);
;             }
.LBB0_1322:
	v_add_u32_e32 v13, s24, v9
	v_mov_b64_e32 v[14:15], s[20:21]
	v_mad_i64_i32 v[14:15], s[4:5], v13, s84, v[14:15]
	v_mov_b32_e32 v13, v145
	v_lshl_add_u64 v[12:13], v[14:15], 0, v[12:13]
	v_add_co_u32_e32 v12, vcc, 0xd601000, v12
	s_nop 1
	v_addc_co_u32_e32 v13, vcc, 0, v13, vcc
	s_waitcnt vmcnt(0)
	v_lshlrev_b32_e32 v20, 16, v158
	v_and_b32_e32 v21, 0xffff0000, v158
	v_lshlrev_b32_e32 v22, 16, v159
	v_and_b32_e32 v23, 0xffff0000, v159
	v_lshlrev_b32_e32 v24, 16, v160
	v_and_b32_e32 v25, 0xffff0000, v160
	v_lshlrev_b32_e32 v26, 16, v161
	v_and_b32_e32 v27, 0xffff0000, v161
	global_load_dwordx4 v[12:15], v[10:11], off offset:3088
	global_load_dwordx4 v[16:19], v[10:11], off offset:3072
	s_waitcnt vmcnt(1)
	v_pk_fma_f32 v[0:1], v[12:13], v[24:25], v[0:1]
	s_waitcnt vmcnt(0)
	v_pk_fma_f32 v[4:5], v[16:17], v[20:21], v[4:5]
	v_pk_fma_f32 v[6:7], v[18:19], v[22:23], v[6:7]
	v_pk_fma_f32 v[2:3], v[14:15], v[26:27], v[2:3]

; #define LAS __attribute__((address_space(3)))
; #define MFMA16(X, Y, ACC) ACC = __builtin_amdgcn_mfma_f32_16x16x32_bf16(X, Y, ACC, 0, 0, 0)
; __device__ __forceinline__ void s5_m3(const Args& a, int l, int tile, LAS unsigned char* lds, int tid, int lane, int wave) {
;     ...
;         const int cb = wave & 3, jh = wave >> 2; const bf16* WG = (const bf16*)(wl + WL_GLU);
;         f32x4 acc[8];
; #pragma unroll
;         for (int jt = 0; jt < 8; ++jt) acc[jt] = (f32x4){0.f, 0.f, 0.f, 0.f};
; #pragma unroll
;         for (int ks = 0; ks < 8; ++ks) {
;             const bf16x8 yv = *(const LAS bf16x8*)(lds + OFF_YS + ((cb * 16 + fr) * 264 + 32 * ks + 8 * fq) * 2);
; #pragma unroll
;             for (int jt = 0; jt < 8; ++jt) { const bf16x8 wv = *(const bf16x8*)(WG + (size_t)(jh * 128 + jt * 16 + fr) * 256 + 32 * ks + 8 * fq); MFMA16(wv, yv, acc[jt]); }
;         }
.LBB0_1498:
	s_ashr_i32 s4, s29, 8
	s_lshl_b32 s0, s28, 4
	v_and_or_b32 v36, s0, 48, v71
	s_lshl_b32 s0, s4, 7
	v_or_b32_e32 v30, s0, v71
	v_readlane_b32 s6, v254, 57
	v_lshlrev_b32_e32 v144, 1, v70
	v_readlane_b32 s7, v254, 58
	v_ashrrev_i32_e32 v31, 31, v30
	s_movk_i32 s1, 0x108
	v_lshl_add_u64 v[54:55], s[6:7], 0, v[144:145]
	v_lshlrev_b64 v[0:1], 9, v[30:31]
	v_mad_u32_u24 v2, v36, s1, v70
	v_lshl_add_u64 v[0:1], v[54:55], 0, v[0:1]
	s_waitcnt lgkmcnt(0)
	s_barrier
	v_lshl_add_u32 v12, v2, 1, s3
	v_mov_b32_e32 v190, 0x2000
	v_mov_b32_e32 v191, 0
	global_load_dwordx4 v[198:201], v[0:1], off
	v_lshl_add_u64 v[2:3], v[0:1], 0, v[190:191]
	global_load_dwordx4 v[202:205], v[2:3], off
	v_lshl_add_u64 v[4:5], v[2:3], 0, v[190:191]
	global_load_dwordx4 v[206:209], v[4:5], off
	v_lshl_add_u64 v[6:7], v[4:5], 0, v[190:191]
	global_load_dwordx4 v[210:213], v[6:7], off
	v_lshl_add_u64 v[8:9], v[6:7], 0, v[190:191]
	global_load_dwordx4 v[214:217], v[8:9], off
	v_lshl_add_u64 v[10:11], v[8:9], 0, v[190:191]
	global_load_dwordx4 v[218:221], v[10:11], off
	v_lshl_add_u64 v[28:29], v[10:11], 0, v[190:191]
	global_load_dwordx4 v[222:225], v[28:29], off
	v_lshl_add_u64 v[30:31], v[28:29], 0, v[190:191]
	global_load_dwordx4 v[226:229], v[30:31], off
	ds_read_b128 v[162:165], v12
	ds_read_b128 v[166:169], v12 offset:64
	v_readlane_b32 s6, v254, 59
	v_readlane_b32 s7, v254, 60
	v_cmp_gt_u32_e32 vcc, 16, v69
	global_load_dwordx4 v[230:233], v[0:1], off offset:64
	global_load_dwordx4 v[234:237], v[2:3], off offset:64
	global_load_dwordx4 v[238:241], v[4:5], off offset:64
	global_load_dwordx4 v[242:245], v[6:7], off offset:64
	global_load_dwordx4 v[246:249], v[8:9], off offset:64
	global_load_dwordx4 v[150:153], v[10:11], off offset:64
	global_load_dwordx4 v[154:157], v[28:29], off offset:64
	global_load_dwordx4 v[158:161], v[30:31], off offset:64
	s_waitcnt vmcnt(15) lgkmcnt(1)
	v_mfma_f32_16x16x32_bf16 v[18:21], v[198:201], v[162:165], 0
	global_load_dwordx4 v[198:201], v[0:1], off offset:128
	s_waitcnt vmcnt(15)
	v_mfma_f32_16x16x32_bf16 v[22:25], v[202:205], v[162:165], 0
	global_load_dwordx4 v[202:205], v[2:3], off offset:128
	s_waitcnt vmcnt(15)
	v_mfma_f32_16x16x32_bf16 v[32:35], v[206:209], v[162:165], 0
	global_load_dwordx4 v[206:209], v[4:5], off offset:128
	s_waitcnt vmcnt(15)
	v_mfma_f32_16x16x32_bf16 v[38:41], v[210:213], v[162:165], 0
	global_load_dwordx4 v[210:213], v[6:7], off offset:128
	s_waitcnt vmcnt(15)
	v_mfma_f32_16x16x32_bf16 v[42:45], v[214:217], v[162:165], 0
	global_load_dwordx4 v[214:217], v[8:9], off offset:128
	s_waitcnt vmcnt(15)
	v_mfma_f32_16x16x32_bf16 v[46:49], v[218:221], v[162:165], 0
	global_load_dwordx4 v[218:221], v[10:11], off offset:128
	s_waitcnt vmcnt(15)
	v_mfma_f32_16x16x32_bf16 v[50:53], v[222:225], v[162:165], 0
	global_load_dwordx4 v[222:225], v[28:29], off offset:128
	s_waitcnt vmcnt(15)
	v_mfma_f32_16x16x32_bf16 v[14:17], v[226:229], v[162:165], 0
	global_load_dwordx4 v[226:229], v[30:31], off offset:128
	ds_read_b128 v[162:165], v12 offset:128
	s_waitcnt vmcnt(15) lgkmcnt(1)
	v_mfma_f32_16x16x32_bf16 v[18:21], v[230:233], v[166:169], v[18:21]
	global_load_dwordx4 v[230:233], v[0:1], off offset:192
	s_waitcnt vmcnt(15)
	v_mfma_f32_16x16x32_bf16 v[22:25], v[234:237], v[166:169], v[22:25]
	global_load_dwordx4 v[234:237], v[2:3], off offset:192
	s_waitcnt vmcnt(15)
	v_mfma_f32_16x16x32_bf16 v[32:35], v[238:241], v[166:169], v[32:35]
	global_load_dwordx4 v[238:241], v[4:5], off offset:192
	s_waitcnt vmcnt(15)
	v_mfma_f32_16x16x32_bf16 v[38:41], v[242:245], v[166:169], v[38:41]
	global_load_dwordx4 v[242:245], v[6:7], off offset:192
	s_waitcnt vmcnt(15)
	v_mfma_f32_16x16x32_bf16 v[42:45], v[246:249], v[166:169], v[42:45]
	global_load_dwordx4 v[246:249], v[8:9], off offset:192
	s_waitcnt vmcnt(15)
	v_mfma_f32_16x16x32_bf16 v[46:49], v[150:153], v[166:169], v[46:49]
	global_load_dwordx4 v[150:153], v[10:11], off offset:192
	s_waitcnt vmcnt(15)
	v_mfma_f32_16x16x32_bf16 v[50:53], v[154:157], v[166:169], v[50:53]
	global_load_dwordx4 v[154:157], v[28:29], off offset:192
	s_waitcnt vmcnt(15)
	v_mfma_f32_16x16x32_bf16 v[14:17], v[158:161], v[166:169], v[14:17]
	global_load_dwordx4 v[158:161], v[30:31], off offset:192
	ds_read_b128 v[166:169], v12 offset:192
	s_waitcnt vmcnt(15) lgkmcnt(1)
	v_mfma_f32_16x16x32_bf16 v[18:21], v[198:201], v[162:165], v[18:21]
	global_load_dwordx4 v[198:201], v[0:1], off offset:256
	s_waitcnt vmcnt(15)
	v_mfma_f32_16x16x32_bf16 v[22:25], v[202:205], v[162:165], v[22:25]
	global_load_dwordx4 v[202:205], v[2:3], off offset:256
	s_waitcnt vmcnt(15)
	v_mfma_f32_16x16x32_bf16 v[32:35], v[206:209], v[162:165], v[32:35]
	global_load_dwordx4 v[206:209], v[4:5], off offset:256
	s_waitcnt vmcnt(15)
	v_mfma_f32_16x16x32_bf16 v[38:41], v[210:213], v[162:165], v[38:41]
	global_load_dwordx4 v[210:213], v[6:7], off offset:256
	s_waitcnt vmcnt(15)
	v_mfma_f32_16x16x32_bf16 v[42:45], v[214:217], v[162:165], v[42:45]
	global_load_dwordx4 v[214:217], v[8:9], off offset:256
	s_waitcnt vmcnt(15)
	v_mfma_f32_16x16x32_bf16 v[46:49], v[218:221], v[162:165], v[46:49]
	global_load_dwordx4 v[218:221], v[10:11], off offset:256
	s_waitcnt vmcnt(15)
	v_mfma_f32_16x16x32_bf16 v[50:53], v[222:225], v[162:165], v[50:53]
	global_load_dwordx4 v[222:225], v[28:29], off offset:256
	s_waitcnt vmcnt(15)
	v_mfma_f32_16x16x32_bf16 v[14:17], v[226:229], v[162:165], v[14:17]
	global_load_dwordx4 v[226:229], v[30:31], off offset:256
	ds_read_b128 v[162:165], v12 offset:256
	s_waitcnt vmcnt(15) lgkmcnt(1)
	v_mfma_f32_16x16x32_bf16 v[18:21], v[230:233], v[166:169], v[18:21]
	global_load_dwordx4 v[230:233], v[0:1], off offset:320
	s_waitcnt vmcnt(15)
; #define LAS __attribute__((address_space(3)))
; __device__ __forceinline__ float sigmoidf_(float x) { return __builtin_amdgcn_rcpf(1.0f + __expf(-x)); }
; #define MFMA16(X, Y, ACC) ACC = __builtin_amdgcn_mfma_f32_16x16x32_bf16(X, Y, ACC, 0, 0, 0)
; __device__ __forceinline__ void s5_m3(const Args& a, int l, int tile, LAS unsigned char* lds, int tid, int lane, int wave) {
;     ...
;         for (int ks = 0; ks < 8; ++ks) {
;             const bf16x8 yv = *(const LAS bf16x8*)(lds + OFF_YS + ((cb * 16 + fr) * 264 + 32 * ks + 8 * fq) * 2);
; #pragma unroll
;             for (int jt = 0; jt < 8; ++jt) { const bf16x8 wv = *(const bf16x8*)(WG + (size_t)(jh * 128 + jt * 16 + fr) * 256 + 32 * ks + 8 * fq); MFMA16(wv, yv, acc[jt]); }
;         }
;     ...
;         for (int jt = 0; jt < 8; ++jt) {
;             const int j0 = jh * 128 + jt * 16 + 4 * fq;
;             const f32x4 bg = *(const f32x4*)(a.in[16] + (size_t)l * 256 + j0);
;             const u32x2 yr = *(const LAS u32x2*)(lds + OFF_YS + (t * 264 + j0) * 2);
;             f32x4 o;
;             o.x = __uint_as_float(yr.x << 16) * sigmoidf_(acc[jt].x + bg.x); o.y = __uint_as_float(yr.x & 0xffff0000u) * sigmoidf_(acc[jt].y + bg.y);
;             o.z = __uint_as_float(yr.y << 16) * sigmoidf_(acc[jt].z + bg.z); o.w = __uint_as_float(yr.y & 0xffff0000u) * sigmoidf_(acc[jt].w + bg.w);
	v_mfma_f32_16x16x32_bf16 v[22:25], v[234:237], v[166:169], v[22:25]
	global_load_dwordx4 v[234:237], v[2:3], off offset:320
	s_waitcnt vmcnt(15)
	v_mfma_f32_16x16x32_bf16 v[32:35], v[238:241], v[166:169], v[32:35]
	global_load_dwordx4 v[238:241], v[4:5], off offset:320
	s_waitcnt vmcnt(15)
	v_mfma_f32_16x16x32_bf16 v[38:41], v[242:245], v[166:169], v[38:41]
	global_load_dwordx4 v[242:245], v[6:7], off offset:320
	s_waitcnt vmcnt(15)
	v_mfma_f32_16x16x32_bf16 v[42:45], v[246:249], v[166:169], v[42:45]
	global_load_dwordx4 v[246:249], v[8:9], off offset:320
	s_waitcnt vmcnt(15)
	v_mfma_f32_16x16x32_bf16 v[46:49], v[150:153], v[166:169], v[46:49]
	global_load_dwordx4 v[150:153], v[10:11], off offset:320
	s_waitcnt vmcnt(15)
	v_mfma_f32_16x16x32_bf16 v[50:53], v[154:157], v[166:169], v[50:53]
	global_load_dwordx4 v[154:157], v[28:29], off offset:320
	s_waitcnt vmcnt(15)
	v_mfma_f32_16x16x32_bf16 v[14:17], v[158:161], v[166:169], v[14:17]
	global_load_dwordx4 v[158:161], v[30:31], off offset:320
	ds_read_b128 v[166:169], v12 offset:320
	s_waitcnt vmcnt(15) lgkmcnt(1)
	v_mfma_f32_16x16x32_bf16 v[18:21], v[198:201], v[162:165], v[18:21]
	global_load_dwordx4 v[198:201], v[0:1], off offset:384
	s_waitcnt vmcnt(15)
	v_mfma_f32_16x16x32_bf16 v[22:25], v[202:205], v[162:165], v[22:25]
	global_load_dwordx4 v[202:205], v[2:3], off offset:384
	s_waitcnt vmcnt(15)
	v_mfma_f32_16x16x32_bf16 v[32:35], v[206:209], v[162:165], v[32:35]
	global_load_dwordx4 v[206:209], v[4:5], off offset:384
	s_waitcnt vmcnt(15)
	v_mfma_f32_16x16x32_bf16 v[38:41], v[210:213], v[162:165], v[38:41]
	global_load_dwordx4 v[210:213], v[6:7], off offset:384
	s_waitcnt vmcnt(15)
	v_mfma_f32_16x16x32_bf16 v[42:45], v[214:217], v[162:165], v[42:45]
	global_load_dwordx4 v[214:217], v[8:9], off offset:384
	s_waitcnt vmcnt(15)
	v_mfma_f32_16x16x32_bf16 v[46:49], v[218:221], v[162:165], v[46:49]
	global_load_dwordx4 v[218:221], v[10:11], off offset:384
	s_waitcnt vmcnt(15)
	v_mfma_f32_16x16x32_bf16 v[50:53], v[222:225], v[162:165], v[50:53]
	global_load_dwordx4 v[222:225], v[28:29], off offset:384
	s_waitcnt vmcnt(15)
	v_mfma_f32_16x16x32_bf16 v[14:17], v[226:229], v[162:165], v[14:17]
	global_load_dwordx4 v[226:229], v[30:31], off offset:384
	ds_read_b128 v[162:165], v12 offset:384
	s_waitcnt vmcnt(15) lgkmcnt(1)
	v_mfma_f32_16x16x32_bf16 v[18:21], v[230:233], v[166:169], v[18:21]
	global_load_dwordx4 v[230:233], v[0:1], off offset:448
	s_waitcnt vmcnt(15)
	v_mfma_f32_16x16x32_bf16 v[22:25], v[234:237], v[166:169], v[22:25]
	global_load_dwordx4 v[234:237], v[2:3], off offset:448
	s_waitcnt vmcnt(15)
	v_mfma_f32_16x16x32_bf16 v[32:35], v[238:241], v[166:169], v[32:35]
	global_load_dwordx4 v[238:241], v[4:5], off offset:448
	s_waitcnt vmcnt(15)
	v_mfma_f32_16x16x32_bf16 v[38:41], v[242:245], v[166:169], v[38:41]
	global_load_dwordx4 v[242:245], v[6:7], off offset:448
	s_waitcnt vmcnt(15)
	v_mfma_f32_16x16x32_bf16 v[42:45], v[246:249], v[166:169], v[42:45]
	global_load_dwordx4 v[246:249], v[8:9], off offset:448
	s_waitcnt vmcnt(15)
	v_mfma_f32_16x16x32_bf16 v[46:49], v[150:153], v[166:169], v[46:49]
	global_load_dwordx4 v[150:153], v[10:11], off offset:448
	s_waitcnt vmcnt(15)
	v_mfma_f32_16x16x32_bf16 v[50:53], v[154:157], v[166:169], v[50:53]
	global_load_dwordx4 v[154:157], v[28:29], off offset:448
	s_waitcnt vmcnt(15)
	v_mfma_f32_16x16x32_bf16 v[14:17], v[158:161], v[166:169], v[14:17]
	global_load_dwordx4 v[158:161], v[30:31], off offset:448
	s_waitcnt vmcnt(15) lgkmcnt(0)
	v_mfma_f32_16x16x32_bf16 v[18:21], v[198:201], v[162:165], v[18:21]
	s_waitcnt vmcnt(14)
	v_mfma_f32_16x16x32_bf16 v[22:25], v[202:205], v[162:165], v[22:25]
	s_waitcnt vmcnt(13)
	v_mfma_f32_16x16x32_bf16 v[32:35], v[206:209], v[162:165], v[32:35]
	s_waitcnt vmcnt(12)
	v_mfma_f32_16x16x32_bf16 v[38:41], v[210:213], v[162:165], v[38:41]
	s_waitcnt vmcnt(11)
	v_mfma_f32_16x16x32_bf16 v[42:45], v[214:217], v[162:165], v[42:45]
	s_waitcnt vmcnt(10)
	v_mfma_f32_16x16x32_bf16 v[46:49], v[218:221], v[162:165], v[46:49]
	s_waitcnt vmcnt(9)
	v_mfma_f32_16x16x32_bf16 v[50:53], v[222:225], v[162:165], v[50:53]
	s_waitcnt vmcnt(8)
	v_mfma_f32_16x16x32_bf16 v[54:57], v[226:229], v[162:165], v[14:17]
	ds_read_b128 v[58:61], v12 offset:448
	s_nop 1
	s_nop 0
	s_waitcnt vmcnt(0) lgkmcnt(0)
	v_mfma_f32_16x16x32_bf16 v[24:27], v[234:237], v[58:61], v[22:25]
	v_mfma_f32_16x16x32_bf16 v[62:65], v[230:233], v[58:61], v[18:21]
	s_waitcnt vmcnt(0)
	v_mfma_f32_16x16x32_bf16 v[20:23], v[238:241], v[58:61], v[32:35]
	s_nop 1
	v_or_b32_e32 v32, s0, v68
	v_ashrrev_i32_e32 v33, 31, v32
	v_lshl_add_u64 v[34:35], v[32:33], 2, s[6:7]
	s_waitcnt vmcnt(0)
	v_mfma_f32_16x16x32_bf16 v[16:19], v[242:245], v[58:61], v[38:41]
	s_waitcnt vmcnt(0)
	v_mfma_f32_16x16x32_bf16 v[12:15], v[246:249], v[58:61], v[42:45]
	s_nop 1
	global_load_dwordx4 v[42:45], v[34:35], off
	s_waitcnt vmcnt(0)
	v_add_f32_e32 v38, v62, v42
	v_mfma_f32_16x16x32_bf16 v[8:11], v[150:153], v[58:61], v[46:49]
	v_mul_f32_e32 v38, 0xbfb8aa3b, v38
	v_exp_f32_e32 v38, v38
	v_mad_u32_u24 v28, v36, s1, v32
	v_lshl_add_u32 v41, v28, 1, s3
	s_waitcnt vmcnt(0)
	v_mfma_f32_16x16x32_bf16 v[4:7], v[154:157], v[58:61], v[50:53]
	ds_read2_b64 v[28:31], v41 offset1:4
	v_add_f32_e32 v38, 1.0, v38
	v_rcp_f32_e32 v38, v38
	v_add_f32_e32 v39, v64, v44
	v_mul_f32_e32 v39, 0xbfb8aa3b, v39
	s_waitcnt lgkmcnt(0)
	v_lshlrev_b32_e32 v37, 16, v28
	v_mul_f32_e32 v37, v38, v37
	v_add_f32_e32 v38, v63, v43
	v_mul_f32_e32 v38, 0xbfb8aa3b, v38
	v_exp_f32_e32 v38, v38
	v_exp_f32_e32 v39, v39
	v_and_b32_e32 v28, 0xffff0000, v28
	s_waitcnt vmcnt(0)
; #define LAS __attribute__((address_space(3)))
; __device__ __forceinline__ float sigmoidf_(float x) { return __builtin_amdgcn_rcpf(1.0f + __expf(-x)); }
; __device__ __forceinline__ void s5_m3(const Args& a, int l, int tile, LAS unsigned char* lds, int tid, int lane, int wave) {
;     ...
;         for (int jt = 0; jt < 8; ++jt) {
;             const int j0 = jh * 128 + jt * 16 + 4 * fq;
;             const f32x4 bg = *(const f32x4*)(a.in[16] + (size_t)l * 256 + j0);
;             const u32x2 yr = *(const LAS u32x2*)(lds + OFF_YS + (t * 264 + j0) * 2);
;             f32x4 o;
;             o.x = __uint_as_float(yr.x << 16) * sigmoidf_(acc[jt].x + bg.x); o.y = __uint_as_float(yr.x & 0xffff0000u) * sigmoidf_(acc[jt].y + bg.y);
;             o.z = __uint_as_float(yr.y << 16) * sigmoidf_(acc[jt].z + bg.z); o.w = __uint_as_float(yr.y & 0xffff0000u) * sigmoidf_(acc[jt].w + bg.w);
;             acc[jt] = o; ss += (o.x * o.x + o.y * o.y) + (o.z * o.z + o.w * o.w);
;         }
	v_mfma_f32_16x16x32_bf16 v[0:3], v[158:161], v[58:61], v[54:57]
	v_add_f32_e32 v38, 1.0, v38
	v_rcp_f32_e32 v38, v38
	v_add_f32_e32 v39, 1.0, v39
	v_rcp_f32_e32 v39, v39
	v_mul_f32_e32 v28, v38, v28
	v_lshlrev_b32_e32 v38, 16, v29
	v_mul_f32_e32 v38, v39, v38
	v_add_f32_e32 v39, v65, v45
	global_load_dwordx4 v[42:45], v[34:35], off offset:64
	v_mul_f32_e32 v39, 0xbfb8aa3b, v39
	v_exp_f32_e32 v39, v39
	v_and_b32_e32 v29, 0xffff0000, v29
	v_add_f32_e32 v39, 1.0, v39
	v_rcp_f32_e32 v39, v39
	s_waitcnt vmcnt(0)
	v_add_f32_e32 v24, v24, v42
	v_mul_f32_e32 v24, 0xbfb8aa3b, v24
	v_add_f32_e32 v25, v25, v43
	v_exp_f32_e32 v24, v24
	v_mul_f32_e32 v25, 0xbfb8aa3b, v25
	v_exp_f32_e32 v25, v25
	v_mul_f32_e32 v29, v39, v29
	v_add_f32_e32 v24, 1.0, v24
	v_rcp_f32_e32 v24, v24
	v_add_f32_e32 v25, 1.0, v25
	v_mul_f32_e32 v39, v28, v28
	v_mul_f32_e32 v40, v29, v29
	v_rcp_f32_e32 v25, v25
	v_fmac_f32_e32 v39, v37, v37
	v_fmac_f32_e32 v40, v38, v38
	v_add_f32_e32 v46, v39, v40
	v_lshlrev_b32_e32 v39, 16, v30
	v_mul_f32_e32 v39, v24, v39
	v_and_b32_e32 v24, 0xffff0000, v30
	v_mul_f32_e32 v30, v25, v24
	v_add_f32_e32 v25, v26, v44
	v_mul_f32_e32 v25, 0xbfb8aa3b, v25
	v_exp_f32_e32 v25, v25
	v_lshlrev_b32_e32 v24, 16, v31
	v_add_f32_e32 v25, 1.0, v25
	v_rcp_f32_e32 v25, v25
	s_nop 0
	v_mul_f32_e32 v40, v25, v24
	v_add_f32_e32 v25, v27, v45
	global_load_dwordx4 v[42:45], v[34:35], off offset:128
	v_mul_f32_e32 v25, 0xbfb8aa3b, v25
	v_exp_f32_e32 v25, v25
	v_and_b32_e32 v24, 0xffff0000, v31
	v_add_f32_e32 v25, 1.0, v25
	v_rcp_f32_e32 v25, v25
	s_waitcnt vmcnt(0)
	v_add_f32_e32 v20, v20, v42
	v_add_f32_e32 v21, v21, v43
	v_add_f32_e32 v22, v22, v44
	v_add_f32_e32 v23, v23, v45
	global_load_dwordx4 v[42:45], v[34:35], off offset:192
	v_mul_f32_e32 v31, v25, v24
	v_mul_f32_e32 v21, 0xbfb8aa3b, v21
	v_mul_f32_e32 v24, v30, v30
	v_mul_f32_e32 v25, v31, v31
	v_exp_f32_e32 v21, v21
	v_mul_f32_e32 v22, 0xbfb8aa3b, v22
	v_fmac_f32_e32 v24, v39, v39
	v_fmac_f32_e32 v25, v40, v40
	v_exp_f32_e32 v22, v22
	v_mul_f32_e32 v23, 0xbfb8aa3b, v23
	v_add_f32_e32 v24, v24, v25
	v_mul_f32_e32 v20, 0xbfb8aa3b, v20
	v_exp_f32_e32 v23, v23
	v_add_f32_e32 v46, v46, v24
	ds_read2_b64 v[24:27], v41 offset0:8 offset1:12
	v_exp_f32_e32 v20, v20
	v_add_f32_e32 v21, 1.0, v21
	v_rcp_f32_e32 v21, v21
	v_add_f32_e32 v22, 1.0, v22
	v_rcp_f32_e32 v22, v22
	v_add_f32_e32 v23, 1.0, v23
	v_add_f32_e32 v20, 1.0, v20
	v_rcp_f32_e32 v23, v23
	s_waitcnt lgkmcnt(0)
	v_lshlrev_b32_e32 v47, 16, v24
	v_rcp_f32_e32 v20, v20
	v_and_b32_e32 v24, 0xffff0000, v24
	v_mul_f32_e32 v21, v21, v24
	v_lshlrev_b32_e32 v24, 16, v25
	v_mul_f32_e32 v22, v22, v24
	v_and_b32_e32 v24, 0xffff0000, v25
	v_mul_f32_e32 v23, v23, v24
	v_mul_f32_e32 v20, v20, v47
	v_mul_f32_e32 v24, v21, v21
	v_mul_f32_e32 v25, v23, v23
	v_fmac_f32_e32 v24, v20, v20
	v_fmac_f32_e32 v25, v22, v22
	v_add_f32_e32 v24, v24, v25
	v_add_f32_e32 v46, v46, v24
	v_lshlrev_b32_e32 v24, 16, v26
	s_waitcnt vmcnt(0)
	v_add_f32_e32 v16, v16, v42
	v_mul_f32_e32 v16, 0xbfb8aa3b, v16
	v_add_f32_e32 v17, v17, v43
	v_exp_f32_e32 v16, v16
	v_mul_f32_e32 v17, 0xbfb8aa3b, v17
	v_exp_f32_e32 v17, v17
	v_add_f32_e32 v16, 1.0, v16
	v_rcp_f32_e32 v16, v16
	v_add_f32_e32 v17, 1.0, v17
	v_rcp_f32_e32 v17, v17
	v_mul_f32_e32 v24, v16, v24
	v_and_b32_e32 v16, 0xffff0000, v26
	v_mul_f32_e32 v25, v17, v16
	v_add_f32_e32 v17, v18, v44
	v_mul_f32_e32 v17, 0xbfb8aa3b, v17
	v_exp_f32_e32 v17, v17
	v_lshlrev_b32_e32 v16, 16, v27
	v_add_f32_e32 v17, 1.0, v17
	v_rcp_f32_e32 v17, v17
	s_nop 0
	v_mul_f32_e32 v26, v17, v16
	v_add_f32_e32 v17, v19, v45
	global_load_dwordx4 v[42:45], v[34:35], off offset:256
	v_mul_f32_e32 v17, 0xbfb8aa3b, v17
	v_exp_f32_e32 v17, v17
	v_and_b32_e32 v16, 0xffff0000, v27
	v_add_f32_e32 v17, 1.0, v17
	v_rcp_f32_e32 v17, v17
	s_waitcnt vmcnt(0)
	v_add_f32_e32 v12, v12, v42
	v_add_f32_e32 v13, v13, v43
	v_add_f32_e32 v14, v14, v44
	v_add_f32_e32 v15, v15, v45
	global_load_dwordx4 v[42:45], v[34:35], off offset:320
	v_mul_f32_e32 v27, v17, v16
	v_mul_f32_e32 v13, 0xbfb8aa3b, v13
	v_mul_f32_e32 v16, v25, v25
	v_mul_f32_e32 v17, v27, v27
	v_exp_f32_e32 v13, v13
	v_mul_f32_e32 v14, 0xbfb8aa3b, v14
	v_fmac_f32_e32 v16, v24, v24
	v_fmac_f32_e32 v17, v26, v26
	v_exp_f32_e32 v14, v14
	v_mul_f32_e32 v15, 0xbfb8aa3b, v15
	v_add_f32_e32 v16, v16, v17
	v_mul_f32_e32 v12, 0xbfb8aa3b, v12
	v_exp_f32_e32 v15, v15
	v_add_f32_e32 v46, v46, v16
	ds_read2_b64 v[16:19], v41 offset0:16 offset1:20
	v_exp_f32_e32 v12, v12
	v_add_f32_e32 v13, 1.0, v13
	v_rcp_f32_e32 v13, v13
	v_add_f32_e32 v14, 1.0, v14
	v_rcp_f32_e32 v14, v14
	v_add_f32_e32 v15, 1.0, v15
	v_add_f32_e32 v12, 1.0, v12
	v_rcp_f32_e32 v15, v15
	s_waitcnt lgkmcnt(0)
; #define LAS __attribute__((address_space(3)))
; __device__ __forceinline__ float sigmoidf_(float x) { return __builtin_amdgcn_rcpf(1.0f + __expf(-x)); }
; __device__ __forceinline__ void s5_m3(const Args& a, int l, int tile, LAS unsigned char* lds, int tid, int lane, int wave) {
;     ...
;         for (int jt = 0; jt < 8; ++jt) {
;             const int j0 = jh * 128 + jt * 16 + 4 * fq;
;             const f32x4 bg = *(const f32x4*)(a.in[16] + (size_t)l * 256 + j0);
;             const u32x2 yr = *(const LAS u32x2*)(lds + OFF_YS + (t * 264 + j0) * 2);
;             f32x4 o;
;             o.x = __uint_as_float(yr.x << 16) * sigmoidf_(acc[jt].x + bg.x); o.y = __uint_as_float(yr.x & 0xffff0000u) * sigmoidf_(acc[jt].y + bg.y);
;             o.z = __uint_as_float(yr.y << 16) * sigmoidf_(acc[jt].z + bg.z); o.w = __uint_as_float(yr.y & 0xffff0000u) * sigmoidf_(acc[jt].w + bg.w);
;             acc[jt] = o; ss += (o.x * o.x + o.y * o.y) + (o.z * o.z + o.w * o.w);
;         }
;         ss += __shfl_xor(ss, 16); ss += __shfl_xor(ss, 32);
;         LAS float* red = (LAS float*)(lds + OFF_RED2);
;         if (fq == 0) red[t * 2 + jh] = ss;
	v_lshlrev_b32_e32 v47, 16, v16
	v_rcp_f32_e32 v12, v12
	v_and_b32_e32 v16, 0xffff0000, v16
	v_mul_f32_e32 v13, v13, v16
	v_lshlrev_b32_e32 v16, 16, v17
	v_mul_f32_e32 v14, v14, v16
	v_and_b32_e32 v16, 0xffff0000, v17
	v_mul_f32_e32 v15, v15, v16
	v_mul_f32_e32 v12, v12, v47
	v_mul_f32_e32 v16, v13, v13
	v_mul_f32_e32 v17, v15, v15
	v_fmac_f32_e32 v16, v12, v12
	v_fmac_f32_e32 v17, v14, v14
	v_add_f32_e32 v16, v16, v17
	v_add_f32_e32 v46, v46, v16
	v_lshlrev_b32_e32 v16, 16, v18
	s_waitcnt vmcnt(0)
	v_add_f32_e32 v8, v8, v42
	v_mul_f32_e32 v8, 0xbfb8aa3b, v8
	v_add_f32_e32 v9, v9, v43
	v_exp_f32_e32 v8, v8
	v_mul_f32_e32 v9, 0xbfb8aa3b, v9
	v_exp_f32_e32 v9, v9
	v_add_f32_e32 v8, 1.0, v8
	v_rcp_f32_e32 v8, v8
	v_add_f32_e32 v9, 1.0, v9
	v_rcp_f32_e32 v9, v9
	v_mul_f32_e32 v16, v8, v16
	v_and_b32_e32 v8, 0xffff0000, v18
	v_mul_f32_e32 v17, v9, v8
	v_add_f32_e32 v9, v10, v44
	v_mul_f32_e32 v9, 0xbfb8aa3b, v9
	v_exp_f32_e32 v9, v9
	v_lshlrev_b32_e32 v8, 16, v19
	v_add_f32_e32 v9, 1.0, v9
	v_rcp_f32_e32 v9, v9
	s_nop 0
	v_mul_f32_e32 v18, v9, v8
	v_add_f32_e32 v9, v11, v45
	global_load_dwordx4 v[42:45], v[34:35], off offset:384
	v_mul_f32_e32 v9, 0xbfb8aa3b, v9
	v_exp_f32_e32 v9, v9
	v_and_b32_e32 v8, 0xffff0000, v19
	v_add_f32_e32 v9, 1.0, v9
	v_rcp_f32_e32 v9, v9
	s_waitcnt vmcnt(0)
	v_add_f32_e32 v4, v4, v42
	v_mul_f32_e32 v19, v9, v8
	v_mul_f32_e32 v4, 0xbfb8aa3b, v4
	v_add_f32_e32 v5, v5, v43
	v_mul_f32_e32 v8, v17, v17
	v_mul_f32_e32 v9, v19, v19
	v_exp_f32_e32 v4, v4
	v_mul_f32_e32 v5, 0xbfb8aa3b, v5
	v_fmac_f32_e32 v8, v16, v16
	v_fmac_f32_e32 v9, v18, v18
	v_exp_f32_e32 v5, v5
	v_add_f32_e32 v8, v8, v9
	v_add_f32_e32 v46, v46, v8
	ds_read2_b64 v[8:11], v41 offset0:24 offset1:28
	v_add_f32_e32 v4, 1.0, v4
	v_rcp_f32_e32 v4, v4
	v_add_f32_e32 v5, 1.0, v5
	v_rcp_f32_e32 v5, v5
	s_waitcnt lgkmcnt(0)
	v_lshlrev_b32_e32 v41, 16, v8
	v_mul_f32_e32 v41, v4, v41
	v_and_b32_e32 v4, 0xffff0000, v8
	v_mul_f32_e32 v8, v5, v4
	v_add_f32_e32 v5, v6, v44
	v_mul_f32_e32 v5, 0xbfb8aa3b, v5
	v_exp_f32_e32 v5, v5
	v_lshlrev_b32_e32 v4, 16, v9
	v_add_f32_e32 v5, 1.0, v5
	v_rcp_f32_e32 v5, v5
	s_nop 0
	v_mul_f32_e32 v42, v5, v4
	v_add_f32_e32 v5, v7, v45
	v_mul_f32_e32 v5, 0xbfb8aa3b, v5
	v_exp_f32_e32 v5, v5
	v_and_b32_e32 v4, 0xffff0000, v9
	v_add_f32_e32 v5, 1.0, v5
	v_rcp_f32_e32 v5, v5
	s_nop 0
	v_mul_f32_e32 v9, v5, v4
	v_mul_f32_e32 v4, v8, v8
	v_mul_f32_e32 v5, v9, v9
	v_fmac_f32_e32 v4, v41, v41
	v_fmac_f32_e32 v5, v42, v42
	v_add_f32_e32 v4, v4, v5
	v_add_f32_e32 v43, v46, v4
	global_load_dwordx4 v[4:7], v[34:35], off offset:448
	v_lshlrev_b32_e32 v34, 16, v10
	s_waitcnt vmcnt(0)
	v_add_f32_e32 v1, v1, v5
	v_mul_f32_e32 v1, 0xbfb8aa3b, v1
	v_add_f32_e32 v2, v2, v6
	v_exp_f32_e32 v1, v1
	v_mul_f32_e32 v2, 0xbfb8aa3b, v2
	v_add_f32_e32 v3, v3, v7
	v_add_f32_e32 v0, v0, v4
	v_exp_f32_e32 v2, v2
	v_mul_f32_e32 v3, 0xbfb8aa3b, v3
	v_mul_f32_e32 v0, 0xbfb8aa3b, v0
	v_exp_f32_e32 v3, v3
	v_exp_f32_e32 v0, v0
	v_add_f32_e32 v1, 1.0, v1
	v_rcp_f32_e32 v1, v1
	v_add_f32_e32 v2, 1.0, v2
	v_rcp_f32_e32 v2, v2
	v_add_f32_e32 v3, 1.0, v3
	v_add_f32_e32 v0, 1.0, v0
	v_rcp_f32_e32 v3, v3
	v_rcp_f32_e32 v0, v0
	v_and_b32_e32 v4, 0xffff0000, v10
	v_mul_f32_e32 v1, v1, v4
	v_lshlrev_b32_e32 v4, 16, v11
	v_mul_f32_e32 v2, v2, v4
	v_and_b32_e32 v4, 0xffff0000, v11
	v_mul_f32_e32 v3, v3, v4
	v_mul_f32_e32 v0, v0, v34
	v_mul_f32_e32 v4, v1, v1
	v_mul_f32_e32 v5, v3, v3
	v_fmac_f32_e32 v4, v0, v0
	v_fmac_f32_e32 v5, v2, v2
	v_add_f32_e32 v4, v4, v5
	v_add_f32_e32 v4, v43, v4
	ds_bpermute_b32 v5, v124, v4
	s_waitcnt lgkmcnt(0)
	v_add_f32_e32 v5, v4, v5
	ds_bpermute_b32 v6, v125, v5
	v_lshlrev_b32_e32 v4, 3, v36
	s_and_saveexec_b64 s[0:1], vcc
	s_cbranch_execz .LBB0_1443
	s_lshl_b32 s4, s4, 2
	s_add_i32 s4, s4, 0
	s_waitcnt lgkmcnt(0)
	v_add_f32_e32 v5, v5, v6
	v_add_u32_e32 v6, s4, v4
	v_add_u32_e32 v6, 0x21400, v6
	ds_write_b32 v6, v5
	s_branch .LBB0_1443
